# attention row-max chains: identity self-max canonicalisations (v_max x,x,x) before the threshold compare deleted (instruction-count trim, exact for non-NaN scores)
# baseline (speedup 1.0000x reference)
; __device__ __forceinline__ void finishSM(f32x16& p0, f32x16& p1, float alpha, float& l_reg, bf16x8& pa0, bf16x8& pa1, bf16x8& pa2, bf16x8& pa3) {
; #pragma unroll
;   for (int r = 0; r < 16; ++r) p1[r] = __builtin_amdgcn_exp2f(p1[r]);
;   float ps = 0;
; #pragma unroll
;   for (int r = 0; r < 16; ++r) ps += p0[r];
; #pragma unroll
;   for (int r = 0; r < 16; ++r) ps += p1[r];
;   { auto rr = __builtin_amdgcn_permlane32_swap(__float_as_uint(ps), __float_as_uint(ps), false, false);
; __device__ __forceinline__ void qkt(f32x16& p0, f32x16& p1, const char* Kn, const char* Kr, const char* Qr, const bf16x8* qr, const f32x16& negm, int lane) {
;   const int kn = (int)(uintptr_t)Kn + (lane & 31) * 16 + (lane >> 5) * 1024, kr = (int)(uintptr_t)Kr + (lane & 31) * 16 + (lane >> 5) * 1024, qa = (int)(uintptr_t)Qr + lane * 16;
;   bf16x8 a0, a1, b0, b1, qa_, qb_;
;     ...
;   a0 = dsr128<0 * 2048>(kn); a1 = dsr128<0 * 2048 + 512>(kn);
;   b0 = dsr128<1 * 2048>(kn); b1 = dsr128<1 * 2048 + 512>(kn); LGKM_W2(2, a0, a1);
;   p0 = __builtin_amdgcn_mfma_f32_32x32x16_bf16(a0, qr[0], negm, 0, 0, 0); p1 = __builtin_amdgcn_mfma_f32_32x32x16_bf16(a1, qr[0], negm, 0, 0, 0);
;   a0 = dsr128<2 * 2048>(kn); a1 = dsr128<2 * 2048 + 512>(kn); LGKM_W2(2, b0, b1); MM(b0, b1, qr[1]);
;   b0 = dsr128<3 * 2048>(kn); b1 = dsr128<3 * 2048 + 512>(kn); LGKM_W2(2, a0, a1); MM(a0, a1, qr[2]);
;   a0 = dsr128<4 * 2048>(kn); a1 = dsr128<4 * 2048 + 512>(kn); LGKM_W2(2, b0, b1); MM(b0, b1, qr[3]);
;   b0 = dsr128<5 * 2048>(kn); b1 = dsr128<5 * 2048 + 512>(kn); LGKM_W2(2, a0, a1); MM(a0, a1, qr[4]);
;   a0 = dsr128<6 * 2048>(kn); a1 = dsr128<6 * 2048 + 512>(kn); LGKM_W2(2, b0, b1); MM(b0, b1, qr[5]);
;   b0 = dsr128<7 * 2048>(kn); b1 = dsr128<7 * 2048 + 512>(kn); LGKM_W2(2, a0, a1); MM(a0, a1, qr[6]);
;   a0 = dsr128<0 * 2048>(kr); a1 = dsr128<0 * 2048 + 512>(kr); qa_ = dsr128<0 * 1024>(qa); LGKM_W2(3, b0, b1); MM(b0, b1, qr[7]);
;   b0 = dsr128<1 * 2048>(kr); b1 = dsr128<1 * 2048 + 512>(kr); qb_ = dsr128<1 * 1024>(qa); LGKM_W3(3, a0, a1, qa_); MM(a0, a1, qa_);
;   a0 = dsr128<2 * 2048>(kr); a1 = dsr128<2 * 2048 + 512>(kr); qa_ = dsr128<2 * 1024>(qa); LGKM_W3(3, b0, b1, qb_); MM(b0, b1, qb_);
;   b0 = dsr128<3 * 2048>(kr); b1 = dsr128<3 * 2048 + 512>(kr); qb_ = dsr128<3 * 1024>(qa); LGKM_W3(3, a0, a1, qa_); MM(a0, a1, qa_);
;   LGKM_W3(0, b0, b1, qb_); MM(b0, b1, qb_);
;     ...
; }
.LBB0_558:
	ds_read_b128 v[98:101], v204 offset:0
	ds_read_b128 v[178:181], v204 offset:0x200
	ds_read_b128 v[210:213], v204 offset:0x800
	ds_read_b128 v[214:217], v204 offset:0xa00
	v_exp_f32_e32 v82, v82
	s_waitcnt lgkmcnt(2)
	v_exp_f32_e32 v83, v83
	v_mfma_f32_32x32x16_bf16 v[114:129], v[98:101], v[130:133], v[66:81]
	v_exp_f32_e32 v84, v84
	v_exp_f32_e32 v85, v85
	v_exp_f32_e32 v86, v86
	v_exp_f32_e32 v87, v87
	v_exp_f32_e32 v88, v88
	v_exp_f32_e32 v89, v89
	v_mfma_f32_32x32x16_bf16 v[98:113], v[178:181], v[130:133], v[66:81]
	v_exp_f32_e32 v90, v90
	ds_read_b128 v[178:181], v204 offset:0x1000
	ds_read_b128 v[218:221], v204 offset:0x1200
	s_waitcnt lgkmcnt(2)
	s_nop 0
	v_mfma_f32_32x32x16_bf16 v[114:129], v[210:213], v[134:137], v[114:129]
	v_add_f32_e32 v251, 0, v172
	v_add_f32_e32 v251, v175, v251
	v_add_f32_e32 v251, v173, v251
	ds_read_b128 v[210:213], v204 offset:0x1800
	v_mfma_f32_32x32x16_bf16 v[98:113], v[214:217], v[134:137], v[98:113]
	v_add_f32_e32 v251, v176, v251
	ds_read_b128 v[214:217], v204 offset:0x1a00
	s_waitcnt lgkmcnt(2)
	s_nop 0
	v_mfma_f32_32x32x16_bf16 v[114:129], v[178:181], v[138:141], v[114:129]
	v_exp_f32_e32 v91, v91
	v_add_f32_e32 v251, v174, v251
	v_add_f32_e32 v251, v177, v251
	ds_read_b128 v[178:181], v204 offset:0x2000
	v_mfma_f32_32x32x16_bf16 v[98:113], v[218:221], v[138:141], v[98:113]
	v_add_f32_e32 v251, v170, v251
	v_add_f32_e32 v251, v171, v251
	ds_read_b128 v[218:221], v204 offset:0x2200
	s_waitcnt lgkmcnt(2)
	s_nop 0
	v_mfma_f32_32x32x16_bf16 v[114:129], v[210:213], v[142:145], v[114:129]
	v_exp_f32_e32 v92, v92
	v_add_f32_e32 v251, v166, v251
	ds_read_b128 v[210:213], v204 offset:0x2800
	v_mfma_f32_32x32x16_bf16 v[98:113], v[214:217], v[142:145], v[98:113]
	v_add_f32_e32 v251, v168, v251
	v_add_f32_e32 v251, v167, v251
	ds_read_b128 v[214:217], v204 offset:0x2a00
	s_waitcnt lgkmcnt(2)
	s_nop 0
	v_mfma_f32_32x32x16_bf16 v[114:129], v[178:181], v[146:149], v[114:129]
	v_add_f32_e32 v251, v169, v251
	v_exp_f32_e32 v93, v93
	ds_read_b128 v[178:181], v204 offset:0x3000
	v_mfma_f32_32x32x16_bf16 v[98:113], v[218:221], v[146:149], v[98:113]
	v_add_f32_e32 v251, v162, v251
	v_add_f32_e32 v251, v164, v251
	ds_read_b128 v[218:221], v204 offset:0x3200
	s_waitcnt lgkmcnt(2)
	s_nop 0
	v_mfma_f32_32x32x16_bf16 v[114:129], v[210:213], v[150:153], v[114:129]
	v_add_f32_e32 v251, v163, v251
	v_add_f32_e32 v251, v165, v251
	ds_read_b128 v[210:213], v204 offset:0x3800
	v_mfma_f32_32x32x16_bf16 v[98:113], v[214:217], v[150:153], v[98:113]
	v_exp_f32_e32 v94, v94
	v_add_f32_e32 v251, v82, v251
	ds_read_b128 v[214:217], v204 offset:0x3a00
	s_waitcnt lgkmcnt(2)
	s_nop 0
	v_mfma_f32_32x32x16_bf16 v[114:129], v[178:181], v[154:157], v[114:129]
	v_add_f32_e32 v251, v83, v251
	v_add_f32_e32 v251, v84, v251
	v_add_f32_e32 v251, v85, v251
	ds_read_b128 v[178:181], v205 offset:0
	v_mfma_f32_32x32x16_bf16 v[98:113], v[218:221], v[154:157], v[98:113]
	v_exp_f32_e32 v95, v95
	v_add_f32_e32 v251, v86, v251
	ds_read_b128 v[218:221], v205 offset:0x200
	ds_read_b128 v[222:225], v189 offset:0
	s_waitcnt lgkmcnt(3)
	s_nop 0
	v_mfma_f32_32x32x16_bf16 v[114:129], v[210:213], v[158:161], v[114:129]
	v_add_f32_e32 v251, v87, v251
	v_add_f32_e32 v251, v88, v251
	ds_read_b128 v[210:213], v205 offset:0x800
	v_mfma_f32_32x32x16_bf16 v[98:113], v[214:217], v[158:161], v[98:113]
	v_add_f32_e32 v251, v89, v251
	v_exp_f32_e32 v96, v96
	ds_read_b128 v[214:217], v205 offset:0xa00
	ds_read_b128 v[226:229], v189 offset:0x400
	s_waitcnt lgkmcnt(3)
	s_nop 0
	v_mfma_f32_32x32x16_bf16 v[114:129], v[178:181], v[222:225], v[114:129]
	v_add_f32_e32 v251, v90, v251
	v_add_f32_e32 v251, v91, v251
	ds_read_b128 v[178:181], v205 offset:0x1000
	v_mfma_f32_32x32x16_bf16 v[98:113], v[218:221], v[222:225], v[98:113]
	v_add_f32_e32 v251, v92, v251
	v_add_f32_e32 v251, v93, v251
	ds_read_b128 v[218:221], v205 offset:0x1200
	ds_read_b128 v[222:225], v189 offset:0x800
	s_waitcnt lgkmcnt(3)
	s_nop 0
	v_mfma_f32_32x32x16_bf16 v[114:129], v[210:213], v[226:229], v[114:129]
	v_exp_f32_e32 v97, v97
	v_add_f32_e32 v251, v94, v251
	ds_read_b128 v[210:213], v205 offset:0x1800
	v_mfma_f32_32x32x16_bf16 v[98:113], v[214:217], v[226:229], v[98:113]
	v_add_f32_e32 v251, v95, v251
	v_add_f32_e32 v251, v96, v251
	v_add_f32_e32 v251, v97, v251
	ds_read_b128 v[214:217], v205 offset:0x1a00
	ds_read_b128 v[226:229], v189 offset:0xc00
	s_waitcnt lgkmcnt(3)
	s_nop 0
	s_waitcnt lgkmcnt(0)
; #define PV_WAIT(n, f) asm volatile("s_waitcnt lgkmcnt(" #n ")" : "+v"(f.l0), "+v"(f.h0), "+v"(f.l1), "+v"(f.h1), "+v"(f.l2), "+v"(f.h2), "+v"(f.l3), "+v"(f.h3) :: "memory")
; template <bool START>
; __device__ __forceinline__ void partialSM(f32x16& p0, f32x16& p1, float& mhat, f32x16& negm, float& alpha) {
;   float pmax = p0[0];
; #pragma unroll
;   for (int r = 1; r < 16; ++r) pmax = fmaxf(pmax, p0[r]);
; #pragma unroll
;   for (int r = 0; r < 16; ++r) pmax = fmaxf(pmax, p1[r]);
;   { auto rr = __builtin_amdgcn_permlane32_swap(__float_as_uint(pmax), __float_as_uint(pmax), false, false);
;     pmax = fmaxf(__uint_as_float(rr[0]), __uint_as_float(rr[1])); }
;   alpha = 1.f;
;   if (START || __builtin_expect(__any(pmax > THRL), 0)) {
;     const float dl = START ? pmax : fmaxf(pmax, 0.f);
;     mhat += dl;
; #pragma unroll
;     for (int r = 0; r < 16; ++r) { p0[r] -= dl; p1[r] -= dl; }
; #pragma unroll
;     for (int r = 0; r < 16; ++r) negm[r] = -mhat;
;     asm volatile("" : "+v"(negm));
;     if (!START) alpha = __builtin_amdgcn_exp2f(-dl);
;   }
; #pragma unroll
;   for (int r = 0; r < 16; ++r) p0[r] = __builtin_amdgcn_exp2f(p0[r]);
; }
; __device__ __forceinline__ void finishSM(f32x16& p0, f32x16& p1, float alpha, float& l_reg, bf16x8& pa0, bf16x8& pa1, bf16x8& pa2, bf16x8& pa3) {
; #pragma unroll
;   for (int r = 0; r < 16; ++r) p1[r] = __builtin_amdgcn_exp2f(p1[r]);
;   float ps = 0;
; #pragma unroll
;   for (int r = 0; r < 16; ++r) ps += p0[r];
; #pragma unroll
;   for (int r = 0; r < 16; ++r) ps += p1[r];
;   { auto rr = __builtin_amdgcn_permlane32_swap(__float_as_uint(ps), __float_as_uint(ps), false, false);
;     ps = __uint_as_float(rr[0]) + __uint_as_float(rr[1]); }
;   l_reg = l_reg * alpha + ps;
;     ...
;   PK4(p0, 0, pa0); PK4(p0, 8, pa1); PK4(p1, 0, pa2); PK4(p1, 8, pa3);
; __device__ __forceinline__ void pv_d0(f32x16* o, int vb, bf16x8 pa0, bf16x8 pa1, bf16x8 pa2, bf16x8 pa3) {
;   VF fa, fb;
;   pv_rd<0>(fa, vb);
;   pv_rd<1>(fb, vb); PV_WAIT(8, fa); pv_mm(o[0], fa, pa0, pa1, pa2, pa3);
;   pv_rd<2>(fa, vb); PV_WAIT(8, fb); pv_mm(o[1], fb, pa0, pa1, pa2, pa3);
;   pv_rd<3>(fb, vb); PV_WAIT(8, fa); pv_mm(o[2], fa, pa0, pa1, pa2, pa3);
;   PV_WAIT(0, fb); pv_mm(o[3], fb, pa0, pa1, pa2, pa3);
; }
	v_mfma_f32_32x32x16_bf16 v[114:129], v[178:181], v[222:225], v[114:129]
	v_cvt_pk_bf16_f32 v178, v90, v91
	v_cvt_pk_bf16_f32 v179, v92, v93
	v_cvt_pk_bf16_f32 v180, v94, v95
	v_cvt_pk_bf16_f32 v181, v96, v97
	v_cvt_pk_bf16_f32 v90, v172, v175
	v_cvt_pk_bf16_f32 v91, v173, v176
	v_cvt_pk_bf16_f32 v92, v174, v177
	v_mfma_f32_32x32x16_bf16 v[98:113], v[218:221], v[222:225], v[98:113]
	v_cvt_pk_bf16_f32 v93, v170, v171
	v_cvt_pk_bf16_f32 v94, v166, v168
	v_cvt_pk_bf16_f32 v95, v167, v169
	v_cvt_pk_bf16_f32 v96, v162, v164
	v_cvt_pk_bf16_f32 v97, v163, v165
	v_cvt_pk_bf16_f32 v174, v82, v83
	v_cvt_pk_bf16_f32 v175, v84, v85
	v_mfma_f32_32x32x16_bf16 v[114:129], v[210:213], v[226:229], v[114:129]
	v_cvt_pk_bf16_f32 v176, v86, v87
	v_cvt_pk_bf16_f32 v177, v88, v89
	v_mov_b32_e32 v210, v251
	v_mov_b32_e32 v211, v251
	s_nop 1
	v_permlane32_swap_b32_e32 v210, v211
	v_permlane32_swap_b32_e32 v90, v92
	v_mfma_f32_32x32x16_bf16 v[98:113], v[214:217], v[226:229], v[98:113]
	v_permlane32_swap_b32_e32 v91, v93
	v_permlane32_swap_b32_e32 v94, v96
	v_permlane32_swap_b32_e32 v95, v97
	v_permlane32_swap_b32_e32 v174, v176
	v_permlane32_swap_b32_e32 v175, v177
	v_permlane32_swap_b32_e32 v178, v180
	v_permlane32_swap_b32_e32 v179, v181
	s_sub_i32 s0, s76, 64
	s_ashr_i32 s1, s0, 31
	s_lshl_b64 s[84:85], s[0:1], 10
	v_lshl_add_u64 v[82:83], v[192:193], 0, s[84:85]
	s_add_i32 s84, s76, 0xffffff80
	s_ashr_i32 s85, s84, 31
	s_lshl_b64 vcc, s[0:1], 7
	s_lshl_b64 s[84:85], s[84:85], 10
	s_add_u32 s84, s33, s84
	s_addc_u32 s85, s82, s85
	global_load_dwordx4 v[162:165], v[82:83], off
	global_load_dwordx4 v[166:169], v[82:83], off offset:128
	v_lshl_add_u64 v[82:83], v[190:191], 0, vcc
	v_lshl_add_u64 v[86:87], v[0:1], 1, s[84:85]
	global_load_dwordx4 v[170:173], v[82:83], off
	s_nop 0
	global_load_dwordx4 v[82:85], v[86:87], off
	v_add_co_u32_e32 v86, vcc, s81, v86
	s_nop 1
	v_addc_co_u32_e32 v87, vcc, 0, v87, vcc
	global_load_dwordx4 v[86:89], v[86:87], off
	ds_read_b64_tr_b16 v[212:213], v202 offset:0
	ds_read_b64_tr_b16 v[214:215], v202 offset:0x800
	ds_read_b64_tr_b16 v[216:217], v202 offset:0x1000
	ds_read_b64_tr_b16 v[218:219], v202 offset:0x1800
	ds_read_b64_tr_b16 v[220:221], v202 offset:0x2000
	ds_read_b64_tr_b16 v[222:223], v202 offset:0x2800
	ds_read_b64_tr_b16 v[224:225], v202 offset:0x3000
	ds_read_b64_tr_b16 v[226:227], v202 offset:0x3800
	ds_read_b64_tr_b16 v[228:229], v202 offset:0x200
	ds_read_b64_tr_b16 v[230:231], v202 offset:0xa00
	ds_read_b64_tr_b16 v[232:233], v202 offset:0x1200
	ds_read_b64_tr_b16 v[234:235], v202 offset:0x1a00
	ds_read_b64_tr_b16 v[236:237], v202 offset:0x2200
	ds_read_b64_tr_b16 v[238:239], v202 offset:0x2a00
	ds_read_b64_tr_b16 v[240:241], v202 offset:0x3200
	ds_read_b64_tr_b16 v[242:243], v202 offset:0x3a00
	s_nop 0
	s_waitcnt lgkmcnt(8)
	s_nop 0
	v_mfma_f32_32x32x16_bf16 v[18:33], v[90:93], v[212:215], v[18:33]
	ds_read_b64_tr_b16 v[212:213], v202 offset:0x400
	ds_read_b64_tr_b16 v[214:215], v202 offset:0xc00
	v_mfma_f32_32x32x16_bf16 v[18:33], v[94:97], v[216:219], v[18:33]
	ds_read_b64_tr_b16 v[216:217], v202 offset:0x1400
	ds_read_b64_tr_b16 v[218:219], v202 offset:0x1c00
	v_mfma_f32_32x32x16_bf16 v[18:33], v[174:177], v[220:223], v[18:33]
	ds_read_b64_tr_b16 v[220:221], v202 offset:0x2400
	ds_read_b64_tr_b16 v[222:223], v202 offset:0x2c00
	v_mfma_f32_32x32x16_bf16 v[18:33], v[178:181], v[224:227], v[18:33]
	ds_read_b64_tr_b16 v[224:225], v202 offset:0x3400
	ds_read_b64_tr_b16 v[226:227], v202 offset:0x3c00
	s_waitcnt lgkmcnt(8)
	s_nop 0
	v_mfma_f32_32x32x16_bf16 v[50:65], v[90:93], v[228:231], v[50:65]
	ds_read_b64_tr_b16 v[228:229], v202 offset:0x600
	ds_read_b64_tr_b16 v[230:231], v202 offset:0xe00
	v_mfma_f32_32x32x16_bf16 v[50:65], v[94:97], v[232:235], v[50:65]
	ds_read_b64_tr_b16 v[232:233], v202 offset:0x1600
	ds_read_b64_tr_b16 v[234:235], v202 offset:0x1e00
	v_mfma_f32_32x32x16_bf16 v[50:65], v[174:177], v[236:239], v[50:65]
	ds_read_b64_tr_b16 v[236:237], v202 offset:0x2600
	ds_read_b64_tr_b16 v[238:239], v202 offset:0x2e00
	v_mfma_f32_32x32x16_bf16 v[50:65], v[178:181], v[240:243], v[50:65]
	ds_read_b64_tr_b16 v[240:241], v202 offset:0x3600
	ds_read_b64_tr_b16 v[242:243], v202 offset:0x3e00
	s_waitcnt lgkmcnt(8)
	s_nop 0
	s_waitcnt lgkmcnt(0)
	v_mfma_f32_32x32x16_bf16 v[34:49], v[90:93], v[212:215], v[34:49]
	v_mfma_f32_32x32x16_bf16 v[2:17], v[90:93], v[228:231], v[2:17]
	v_max_f32_e32 v90, v115, v115
	v_max_f32_e32 v91, v114, v114
	v_max_f32_e32 v90, v91, v90
	v_max3_f32 v90, v90, v116, v117
	v_max3_f32 v90, v90, v118, v119
	v_max3_f32 v90, v90, v120, v121
	v_max3_f32 v90, v90, v122, v123
	v_mfma_f32_32x32x16_bf16 v[34:49], v[94:97], v[216:219], v[34:49]
	v_max3_f32 v90, v90, v124, v125
	v_max3_f32 v90, v90, v126, v127
	v_max3_f32 v90, v90, v128, v129
	v_max3_f32 v90, v90, v98, v99
	v_max3_f32 v90, v90, v100, v101
	v_max3_f32 v90, v90, v102, v103
	v_max3_f32 v90, v90, v104, v105
	v_mfma_f32_32x32x16_bf16 v[2:17], v[94:97], v[232:235], v[2:17]
	v_max3_f32 v90, v90, v106, v107
	v_max3_f32 v90, v90, v108, v109
	v_max3_f32 v90, v90, v110, v111
	v_max3_f32 v90, v90, v112, v113
	v_mov_b32_e32 v91, v90
	s_nop 1
	v_permlane32_swap_b32_e32 v90, v91
	v_mfma_f32_32x32x16_bf16 v[34:49], v[174:177], v[220:223], v[34:49]
	v_max_f32_e32 v90, v90, v91
	v_cmp_lt_f32_e32 vcc, s89, v90
	v_mfma_f32_32x32x16_bf16 v[2:17], v[174:177], v[236:239], v[2:17]
	v_mfma_f32_32x32x16_bf16 v[34:49], v[178:181], v[224:227], v[34:49]
	v_mfma_f32_32x32x16_bf16 v[2:17], v[178:181], v[240:243], v[2:17]
	s_cbranch_vccnz .LBB0_576
	v_mov_b32_e32 v212, 1.0
	s_branch .LBB0_563

; template <bool START>
; __device__ __forceinline__ void partialSM(f32x16& p0, f32x16& p1, float& mhat, f32x16& negm, float& alpha) {
;   float pmax = p0[0];
; #pragma unroll
;   for (int r = 1; r < 16; ++r) pmax = fmaxf(pmax, p0[r]);
; #pragma unroll
;   for (int r = 0; r < 16; ++r) pmax = fmaxf(pmax, p1[r]);
;   { auto rr = __builtin_amdgcn_permlane32_swap(__float_as_uint(pmax), __float_as_uint(pmax), false, false);
;     pmax = fmaxf(__uint_as_float(rr[0]), __uint_as_float(rr[1])); }
;   alpha = 1.f;
;   if (START || __builtin_expect(__any(pmax > THRL), 0)) {
;     const float dl = START ? pmax : fmaxf(pmax, 0.f);
;     mhat += dl;
; #pragma unroll
;     for (int r = 0; r < 16; ++r) { p0[r] -= dl; p1[r] -= dl; }
; #pragma unroll
;     for (int r = 0; r < 16; ++r) negm[r] = -mhat;
;     asm volatile("" : "+v"(negm));
;     if (!START) alpha = __builtin_amdgcn_exp2f(-dl);
;   }
; #pragma unroll
;   for (int r = 0; r < 16; ++r) p0[r] = __builtin_amdgcn_exp2f(p0[r]);
; }
; __device__ __forceinline__ void finishSM(f32x16& p0, f32x16& p1, float alpha, float& l_reg, bf16x8& pa0, bf16x8& pa1, bf16x8& pa2, bf16x8& pa3) {
; #pragma unroll
;   for (int r = 0; r < 16; ++r) p1[r] = __builtin_amdgcn_exp2f(p1[r]);
;   float ps = 0;
; #pragma unroll
;   for (int r = 0; r < 16; ++r) ps += p0[r];
; #pragma unroll
;   for (int r = 0; r < 16; ++r) ps += p1[r];
;   { auto rr = __builtin_amdgcn_permlane32_swap(__float_as_uint(ps), __float_as_uint(ps), false, false);
;     ps = __uint_as_float(rr[0]) + __uint_as_float(rr[1]); }
;   l_reg = l_reg * alpha + ps;
;     ...
;   PK4(p0, 0, pa0); PK4(p0, 8, pa1); PK4(p1, 0, pa2); PK4(p1, 8, pa3);
;     ...
; }
; __device__ __forceinline__ void kmask(f32x16& p0, f32x16& p1, int nv, int hi) {
; #pragma unroll
;   for (int r = 0; r < 16; ++r) { const int k = crow(r, hi); if (k >= nv) p0[r] = -1e30f; if (k + 32 >= nv) p1[r] = -1e30f; }
; }
; __device__ __forceinline__ void pv_d0(f32x16* o, int vb, bf16x8 pa0, bf16x8 pa1, bf16x8 pa2, bf16x8 pa3) {
;   VF fa, fb;
;   pv_rd<0>(fa, vb);
;   pv_rd<1>(fb, vb); PV_WAIT(8, fa); pv_mm(o[0], fa, pa0, pa1, pa2, pa3);
;   pv_rd<2>(fa, vb); PV_WAIT(8, fb); pv_mm(o[1], fb, pa0, pa1, pa2, pa3);
;   pv_rd<3>(fb, vb); PV_WAIT(8, fa); pv_mm(o[2], fa, pa0, pa1, pa2, pa3);
;   PV_WAIT(0, fb); pv_mm(o[3], fb, pa0, pa1, pa2, pa3);
; }
.LBB0_565:
	s_lshl_b64 s[84:85], vcc, 1
	s_add_u32 s84, s33, s84
	s_addc_u32 s85, s82, s85
	v_lshl_add_u64 v[98:99], v[0:1], 1, s[84:85]
	v_add_co_u32_e32 v102, vcc, s81, v98
	s_nop 1
	v_addc_co_u32_e32 v103, vcc, 0, v99, vcc
	global_load_dwordx4 v[98:101], v[98:99], off
	s_nop 0
	global_load_dwordx4 v[102:105], v[102:103], off
	ds_read_b64_tr_b16 v[216:217], v207 offset:0
	ds_read_b64_tr_b16 v[218:219], v207 offset:0x800
	ds_read_b64_tr_b16 v[220:221], v207 offset:0x1000
	ds_read_b64_tr_b16 v[222:223], v207 offset:0x1800
	ds_read_b64_tr_b16 v[224:225], v207 offset:0x2000
	ds_read_b64_tr_b16 v[226:227], v207 offset:0x2800
	ds_read_b64_tr_b16 v[228:229], v207 offset:0x3000
	ds_read_b64_tr_b16 v[230:231], v207 offset:0x3800
	ds_read_b64_tr_b16 v[232:233], v207 offset:0x200
	ds_read_b64_tr_b16 v[234:235], v207 offset:0xa00
	ds_read_b64_tr_b16 v[236:237], v207 offset:0x1200
	ds_read_b64_tr_b16 v[238:239], v207 offset:0x1a00
	ds_read_b64_tr_b16 v[240:241], v207 offset:0x2200
	ds_read_b64_tr_b16 v[242:243], v207 offset:0x2a00
	ds_read_b64_tr_b16 v[244:245], v207 offset:0x3200
	ds_read_b64_tr_b16 v[246:247], v207 offset:0x3a00
	s_nop 0
	s_waitcnt lgkmcnt(8)
	s_cmp_lg_u32 s75, s83
	v_mfma_f32_32x32x16_bf16 v[18:33], v[106:109], v[216:219], v[18:33]
	ds_read_b64_tr_b16 v[216:217], v207 offset:0x400
	ds_read_b64_tr_b16 v[218:219], v207 offset:0xc00
	v_mfma_f32_32x32x16_bf16 v[18:33], v[110:113], v[220:223], v[18:33]
	ds_read_b64_tr_b16 v[220:221], v207 offset:0x1400
	ds_read_b64_tr_b16 v[222:223], v207 offset:0x1c00
	v_mfma_f32_32x32x16_bf16 v[18:33], v[174:177], v[224:227], v[18:33]
	ds_read_b64_tr_b16 v[224:225], v207 offset:0x2400
	ds_read_b64_tr_b16 v[226:227], v207 offset:0x2c00
	v_mfma_f32_32x32x16_bf16 v[18:33], v[178:181], v[228:231], v[18:33]
	ds_read_b64_tr_b16 v[228:229], v207 offset:0x3400
	ds_read_b64_tr_b16 v[230:231], v207 offset:0x3c00
	s_waitcnt lgkmcnt(8)
	s_nop 0
	v_mfma_f32_32x32x16_bf16 v[50:65], v[106:109], v[232:235], v[50:65]
	ds_read_b64_tr_b16 v[232:233], v207 offset:0x600
	ds_read_b64_tr_b16 v[234:235], v207 offset:0xe00
	v_mfma_f32_32x32x16_bf16 v[50:65], v[110:113], v[236:239], v[50:65]
	ds_read_b64_tr_b16 v[236:237], v207 offset:0x1600
	ds_read_b64_tr_b16 v[238:239], v207 offset:0x1e00
	v_mfma_f32_32x32x16_bf16 v[50:65], v[174:177], v[240:243], v[50:65]
	ds_read_b64_tr_b16 v[240:241], v207 offset:0x2600
	ds_read_b64_tr_b16 v[242:243], v207 offset:0x2e00
	v_mfma_f32_32x32x16_bf16 v[50:65], v[178:181], v[244:247], v[50:65]
	ds_read_b64_tr_b16 v[244:245], v207 offset:0x3600
	ds_read_b64_tr_b16 v[246:247], v207 offset:0x3e00
	s_waitcnt lgkmcnt(8)
	s_nop 0
	s_waitcnt lgkmcnt(0)
	v_mfma_f32_32x32x16_bf16 v[34:49], v[106:109], v[216:219], v[34:49]
	v_mfma_f32_32x32x16_bf16 v[2:17], v[106:109], v[232:235], v[2:17]
	v_max_f32_e32 v106, v115, v115
	v_max_f32_e32 v107, v114, v114
	v_max_f32_e32 v106, v107, v106
	v_max3_f32 v106, v106, v116, v117
	v_max3_f32 v106, v106, v118, v119
	v_mfma_f32_32x32x16_bf16 v[34:49], v[110:113], v[220:223], v[34:49]
	v_max3_f32 v106, v106, v120, v121
	v_max3_f32 v106, v106, v122, v123
	v_max3_f32 v106, v106, v124, v125
	v_max3_f32 v106, v106, v126, v127
	v_max3_f32 v106, v106, v128, v129
	v_mfma_f32_32x32x16_bf16 v[2:17], v[110:113], v[236:239], v[2:17]
	v_max3_f32 v106, v106, v82, v83
	v_max3_f32 v106, v106, v84, v85
	v_max3_f32 v106, v106, v86, v87
	v_max3_f32 v106, v106, v88, v89
	v_max3_f32 v106, v106, v90, v91
	v_mfma_f32_32x32x16_bf16 v[34:49], v[174:177], v[224:227], v[34:49]
	v_max3_f32 v106, v106, v92, v93
	v_max3_f32 v106, v106, v94, v95
	v_max3_f32 v106, v106, v96, v97
	v_mfma_f32_32x32x16_bf16 v[2:17], v[174:177], v[240:243], v[2:17]
	v_mov_b32_e32 v107, v106
	s_nop 1
	v_permlane32_swap_b32_e32 v106, v107
	v_mfma_f32_32x32x16_bf16 v[34:49], v[178:181], v[228:231], v[34:49]
	v_max_f32_e32 v107, v106, v107
	v_cmp_lt_f32_e32 vcc, s89, v107
	v_mov_b32_e32 v106, 1.0
	v_mfma_f32_32x32x16_bf16 v[2:17], v[178:181], v[244:247], v[2:17]
	s_cbranch_scc1 .LBB0_567
	v_cndmask_b32_e64 v129, v194, v129, s[4:5]
	v_cndmask_b32_e64 v128, v194, v128, s[8:9]
	v_cndmask_b32_e64 v127, v194, v127, s[10:11]
	v_cndmask_b32_e64 v126, v194, v126, s[12:13]
	v_cndmask_b32_e64 v125, v194, v125, s[14:15]
	v_cndmask_b32_e64 v124, v194, v124, s[16:17]
	v_cndmask_b32_e64 v123, v194, v123, s[18:19]
	v_cndmask_b32_e64 v122, v194, v122, s[20:21]
	v_cndmask_b32_e64 v121, v194, v121, s[22:23]
	v_cndmask_b32_e64 v120, v194, v120, s[24:25]
	v_cndmask_b32_e64 v119, v194, v119, s[26:27]
	v_cndmask_b32_e64 v118, v194, v118, s[28:29]
	v_cndmask_b32_e64 v117, v194, v117, s[30:31]
	v_cndmask_b32_e64 v116, v194, v116, s[34:35]
	v_cndmask_b32_e64 v115, v194, v115, s[36:37]
	v_cndmask_b32_e64 v114, v194, v114, s[38:39]
	v_cndmask_b32_e64 v97, v194, v97, s[6:7]
	v_cndmask_b32_e64 v96, v194, v96, s[40:41]
	v_cndmask_b32_e64 v95, v194, v95, s[42:43]
	v_cndmask_b32_e64 v94, v194, v94, s[44:45]
	v_cndmask_b32_e64 v93, v194, v93, s[46:47]
	v_cndmask_b32_e64 v92, v194, v92, s[48:49]
	v_cndmask_b32_e64 v91, v194, v91, s[50:51]
	v_cndmask_b32_e64 v90, v194, v90, s[52:53]
	v_cndmask_b32_e64 v89, v194, v89, s[54:55]
	v_cndmask_b32_e64 v88, v194, v88, s[56:57]
	v_cndmask_b32_e64 v87, v194, v87, s[58:59]
	v_cndmask_b32_e64 v86, v194, v86, s[60:61]
	v_cndmask_b32_e64 v85, v194, v85, s[62:63]
	v_cndmask_b32_e64 v84, v194, v84, s[64:65]
	v_cndmask_b32_e64 v83, v194, v83, s[66:67]
	v_cndmask_b32_e64 v82, v194, v82, s[68:69]
	v_max_f32_e32 v106, v115, v115
	v_max_f32_e32 v107, v114, v114
	v_max_f32_e32 v106, v107, v106
	v_max3_f32 v106, v106, v116, v117
	v_max3_f32 v106, v106, v118, v119
	v_max3_f32 v106, v106, v120, v121
	v_max3_f32 v106, v106, v122, v123
	v_max3_f32 v106, v106, v124, v125
	v_max3_f32 v106, v106, v126, v127
	v_max3_f32 v106, v106, v128, v129
	v_max3_f32 v106, v106, v82, v83
	v_max3_f32 v106, v106, v84, v85
	v_max3_f32 v106, v106, v86, v87
	v_max3_f32 v106, v106, v88, v89
	v_max3_f32 v106, v106, v90, v91
	v_max3_f32 v106, v106, v92, v93
	v_max3_f32 v106, v106, v94, v95
	v_max3_f32 v106, v106, v96, v97
	v_mov_b32_e32 v107, v106
	s_nop 1
	v_permlane32_swap_b32_e32 v106, v107
	v_max_f32_e32 v107, v106, v107
	v_cmp_lt_f32_e32 vcc, s89, v107
	v_mov_b32_e32 v106, 1.0

; __device__ __forceinline__ void finishSM(f32x16& p0, f32x16& p1, float alpha, float& l_reg, bf16x8& pa0, bf16x8& pa1, bf16x8& pa2, bf16x8& pa3) {
; #pragma unroll
;   for (int r = 0; r < 16; ++r) p1[r] = __builtin_amdgcn_exp2f(p1[r]);
;   float ps = 0;
; #pragma unroll
;   for (int r = 0; r < 16; ++r) ps += p0[r];
; #pragma unroll
;   for (int r = 0; r < 16; ++r) ps += p1[r];
;   { auto rr = __builtin_amdgcn_permlane32_swap(__float_as_uint(ps), __float_as_uint(ps), false, false);
; __device__ __forceinline__ void qkt(f32x16& p0, f32x16& p1, const char* Kn, const char* Kr, const char* Qr, const bf16x8* qr, const f32x16& negm, int lane) {
;   const int kn = (int)(uintptr_t)Kn + (lane & 31) * 16 + (lane >> 5) * 1024, kr = (int)(uintptr_t)Kr + (lane & 31) * 16 + (lane >> 5) * 1024, qa = (int)(uintptr_t)Qr + lane * 16;
;   bf16x8 a0, a1, b0, b1, qa_, qb_;
;     ...
;   a0 = dsr128<0 * 2048>(kn); a1 = dsr128<0 * 2048 + 512>(kn);
;   b0 = dsr128<1 * 2048>(kn); b1 = dsr128<1 * 2048 + 512>(kn); LGKM_W2(2, a0, a1);
;   p0 = __builtin_amdgcn_mfma_f32_32x32x16_bf16(a0, qr[0], negm, 0, 0, 0); p1 = __builtin_amdgcn_mfma_f32_32x32x16_bf16(a1, qr[0], negm, 0, 0, 0);
;   a0 = dsr128<2 * 2048>(kn); a1 = dsr128<2 * 2048 + 512>(kn); LGKM_W2(2, b0, b1); MM(b0, b1, qr[1]);
;   b0 = dsr128<3 * 2048>(kn); b1 = dsr128<3 * 2048 + 512>(kn); LGKM_W2(2, a0, a1); MM(a0, a1, qr[2]);
;   a0 = dsr128<4 * 2048>(kn); a1 = dsr128<4 * 2048 + 512>(kn); LGKM_W2(2, b0, b1); MM(b0, b1, qr[3]);
;   b0 = dsr128<5 * 2048>(kn); b1 = dsr128<5 * 2048 + 512>(kn); LGKM_W2(2, a0, a1); MM(a0, a1, qr[4]);
;   a0 = dsr128<6 * 2048>(kn); a1 = dsr128<6 * 2048 + 512>(kn); LGKM_W2(2, b0, b1); MM(b0, b1, qr[5]);
;   b0 = dsr128<7 * 2048>(kn); b1 = dsr128<7 * 2048 + 512>(kn); LGKM_W2(2, a0, a1); MM(a0, a1, qr[6]);
;   a0 = dsr128<0 * 2048>(kr); a1 = dsr128<0 * 2048 + 512>(kr); qa_ = dsr128<0 * 1024>(qa); LGKM_W2(3, b0, b1); MM(b0, b1, qr[7]);
;   b0 = dsr128<1 * 2048>(kr); b1 = dsr128<1 * 2048 + 512>(kr); qb_ = dsr128<1 * 1024>(qa); LGKM_W3(3, a0, a1, qa_); MM(a0, a1, qa_);
;   a0 = dsr128<2 * 2048>(kr); a1 = dsr128<2 * 2048 + 512>(kr); qa_ = dsr128<2 * 1024>(qa); LGKM_W3(3, b0, b1, qb_); MM(b0, b1, qb_);
;   b0 = dsr128<3 * 2048>(kr); b1 = dsr128<3 * 2048 + 512>(kr); qb_ = dsr128<3 * 1024>(qa); LGKM_W3(3, a0, a1, qa_); MM(a0, a1, qa_);
;   LGKM_W3(0, b0, b1, qb_); MM(b0, b1, qb_);
.LBB0_1372:
	ds_read_b128 v[98:101], v211 offset:0
	ds_read_b128 v[178:181], v211 offset:0x200
	ds_read_b128 v[192:195], v211 offset:0x800
	ds_read_b128 v[216:219], v211 offset:0xa00
	v_add_f32_e32 v0, 0, v172
	s_waitcnt lgkmcnt(2)
	v_add_f32_e32 v0, v175, v0
	v_mfma_f32_32x32x16_bf16 v[114:129], v[98:101], v[130:133], v[66:81]
	v_add_f32_e32 v0, v173, v0
	v_add_f32_e32 v0, v176, v0
	v_add_f32_e32 v0, v174, v0
	v_add_f32_e32 v0, v177, v0
	v_add_f32_e32 v0, v170, v0
	v_add_f32_e32 v0, v171, v0
	v_add_f32_e32 v0, v166, v0
	v_mfma_f32_32x32x16_bf16 v[98:113], v[178:181], v[130:133], v[66:81]
	ds_read_b128 v[178:181], v211 offset:0x1000
	ds_read_b128 v[220:223], v211 offset:0x1200
	s_waitcnt lgkmcnt(2)
	v_add_f32_e32 v0, v168, v0
	v_add_f32_e32 v0, v167, v0
	v_add_f32_e32 v0, v169, v0
	v_exp_f32_e32 v82, v82
	v_mfma_f32_32x32x16_bf16 v[114:129], v[192:195], v[134:137], v[114:129]
	ds_read_b128 v[192:195], v211 offset:0x1800
	v_add_f32_e32 v0, v162, v0
	v_exp_f32_e32 v83, v83
	v_add_f32_e32 v0, v164, v0
	v_exp_f32_e32 v84, v84
	v_add_f32_e32 v0, v163, v0
	v_exp_f32_e32 v85, v85
	v_mfma_f32_32x32x16_bf16 v[98:113], v[216:219], v[134:137], v[98:113]
	ds_read_b128 v[216:219], v211 offset:0x1a00
	s_waitcnt lgkmcnt(2)
	v_add_f32_e32 v0, v165, v0
	v_exp_f32_e32 v86, v86
	v_add_f32_e32 v0, v82, v0
	v_exp_f32_e32 v87, v87
	v_add_f32_e32 v0, v83, v0
	v_mfma_f32_32x32x16_bf16 v[114:129], v[178:181], v[138:141], v[114:129]
	ds_read_b128 v[178:181], v211 offset:0x2000
	v_exp_f32_e32 v88, v88
	v_add_f32_e32 v0, v84, v0
	v_exp_f32_e32 v89, v89
	v_add_f32_e32 v0, v85, v0
	v_add_f32_e32 v0, v86, v0
	v_add_f32_e32 v0, v87, v0
	v_mfma_f32_32x32x16_bf16 v[98:113], v[220:223], v[138:141], v[98:113]
	ds_read_b128 v[220:223], v211 offset:0x2200
	s_waitcnt lgkmcnt(2)
	v_add_f32_e32 v0, v88, v0
	v_add_f32_e32 v0, v89, v0
	v_mfma_f32_32x32x16_bf16 v[114:129], v[192:195], v[142:145], v[114:129]
	ds_read_b128 v[192:195], v211 offset:0x2800
	v_mfma_f32_32x32x16_bf16 v[98:113], v[216:219], v[142:145], v[98:113]
	ds_read_b128 v[216:219], v211 offset:0x2a00
	s_waitcnt lgkmcnt(2)
	s_nop 0
	v_mfma_f32_32x32x16_bf16 v[114:129], v[178:181], v[146:149], v[114:129]
	ds_read_b128 v[178:181], v211 offset:0x3000
	v_mfma_f32_32x32x16_bf16 v[98:113], v[220:223], v[146:149], v[98:113]
	ds_read_b128 v[220:223], v211 offset:0x3200
	s_waitcnt lgkmcnt(2)
	s_nop 0
	v_mfma_f32_32x32x16_bf16 v[114:129], v[192:195], v[150:153], v[114:129]
	ds_read_b128 v[192:195], v211 offset:0x3800
	v_mfma_f32_32x32x16_bf16 v[98:113], v[216:219], v[150:153], v[98:113]
	ds_read_b128 v[216:219], v211 offset:0x3a00
	s_waitcnt lgkmcnt(2)
	s_nop 0
	v_mfma_f32_32x32x16_bf16 v[114:129], v[178:181], v[154:157], v[114:129]
	ds_read_b128 v[178:181], v212 offset:0
	v_mfma_f32_32x32x16_bf16 v[98:113], v[220:223], v[154:157], v[98:113]
	ds_read_b128 v[220:223], v212 offset:0x200
	ds_read_b128 v[224:227], v201 offset:0
	s_waitcnt lgkmcnt(3)
	s_nop 0
	v_mfma_f32_32x32x16_bf16 v[114:129], v[192:195], v[158:161], v[114:129]
	ds_read_b128 v[192:195], v212 offset:0x800
	v_mfma_f32_32x32x16_bf16 v[98:113], v[216:219], v[158:161], v[98:113]
	ds_read_b128 v[216:219], v212 offset:0xa00
	ds_read_b128 v[228:231], v201 offset:0x400
	s_waitcnt lgkmcnt(3)
	s_nop 0
	v_mfma_f32_32x32x16_bf16 v[114:129], v[178:181], v[224:227], v[114:129]
	ds_read_b128 v[178:181], v212 offset:0x1000
	v_mfma_f32_32x32x16_bf16 v[98:113], v[220:223], v[224:227], v[98:113]
	ds_read_b128 v[220:223], v212 offset:0x1200
	ds_read_b128 v[224:227], v201 offset:0x800
	s_waitcnt lgkmcnt(3)
	s_nop 0
	v_mfma_f32_32x32x16_bf16 v[114:129], v[192:195], v[228:231], v[114:129]
	ds_read_b128 v[192:195], v212 offset:0x1800
	v_mfma_f32_32x32x16_bf16 v[98:113], v[216:219], v[228:231], v[98:113]
	ds_read_b128 v[216:219], v212 offset:0x1a00
	ds_read_b128 v[228:231], v201 offset:0xc00
	s_waitcnt lgkmcnt(3)
	s_nop 0
	s_waitcnt lgkmcnt(0)
; #define PV_WAIT(n, f) asm volatile("s_waitcnt lgkmcnt(" #n ")" : "+v"(f.l0), "+v"(f.h0), "+v"(f.l1), "+v"(f.h1), "+v"(f.l2), "+v"(f.h2), "+v"(f.l3), "+v"(f.h3) :: "memory")
; template <bool START>
; __device__ __forceinline__ void partialSM(f32x16& p0, f32x16& p1, float& mhat, f32x16& negm, float& alpha) {
;   float pmax = p0[0];
; #pragma unroll
;   for (int r = 1; r < 16; ++r) pmax = fmaxf(pmax, p0[r]);
; #pragma unroll
;   for (int r = 0; r < 16; ++r) pmax = fmaxf(pmax, p1[r]);
;   { auto rr = __builtin_amdgcn_permlane32_swap(__float_as_uint(pmax), __float_as_uint(pmax), false, false);
;     pmax = fmaxf(__uint_as_float(rr[0]), __uint_as_float(rr[1])); }
;   alpha = 1.f;
;   if (START || __builtin_expect(__any(pmax > THRL), 0)) {
;     const float dl = START ? pmax : fmaxf(pmax, 0.f);
;     mhat += dl;
; #pragma unroll
;     for (int r = 0; r < 16; ++r) { p0[r] -= dl; p1[r] -= dl; }
; #pragma unroll
;     for (int r = 0; r < 16; ++r) negm[r] = -mhat;
;     asm volatile("" : "+v"(negm));
;     if (!START) alpha = __builtin_amdgcn_exp2f(-dl);
;   }
; #pragma unroll
;   for (int r = 0; r < 16; ++r) p0[r] = __builtin_amdgcn_exp2f(p0[r]);
; }
; __device__ __forceinline__ void finishSM(f32x16& p0, f32x16& p1, float alpha, float& l_reg, bf16x8& pa0, bf16x8& pa1, bf16x8& pa2, bf16x8& pa3) {
; #pragma unroll
;   for (int r = 0; r < 16; ++r) p1[r] = __builtin_amdgcn_exp2f(p1[r]);
;   float ps = 0;
; #pragma unroll
;   for (int r = 0; r < 16; ++r) ps += p0[r];
; #pragma unroll
;   for (int r = 0; r < 16; ++r) ps += p1[r];
;   { auto rr = __builtin_amdgcn_permlane32_swap(__float_as_uint(ps), __float_as_uint(ps), false, false);
;     ps = __uint_as_float(rr[0]) + __uint_as_float(rr[1]); }
;   l_reg = l_reg * alpha + ps;
;     ...
;   PK4(p0, 0, pa0); PK4(p0, 8, pa1); PK4(p1, 0, pa2); PK4(p1, 8, pa3);
; __device__ __forceinline__ void pv_d0(f32x16* o, int vb, bf16x8 pa0, bf16x8 pa1, bf16x8 pa2, bf16x8 pa3) {
;   VF fa, fb;
;   pv_rd<0>(fa, vb);
;   pv_rd<1>(fb, vb); PV_WAIT(8, fa); pv_mm(o[0], fa, pa0, pa1, pa2, pa3);
;   pv_rd<2>(fa, vb); PV_WAIT(8, fb); pv_mm(o[1], fb, pa0, pa1, pa2, pa3);
;   pv_rd<3>(fb, vb); PV_WAIT(8, fa); pv_mm(o[2], fa, pa0, pa1, pa2, pa3);
;   PV_WAIT(0, fb); pv_mm(o[3], fb, pa0, pa1, pa2, pa3);
; }
	v_mfma_f32_32x32x16_bf16 v[114:129], v[178:181], v[224:227], v[114:129]
	v_exp_f32_e32 v178, v90
	v_exp_f32_e32 v179, v91
	v_exp_f32_e32 v180, v92
	v_exp_f32_e32 v181, v93
	v_add_f32_e32 v0, v178, v0
	v_add_f32_e32 v0, v179, v0
	v_add_f32_e32 v0, v180, v0
	v_mfma_f32_32x32x16_bf16 v[98:113], v[220:223], v[224:227], v[98:113]
	v_add_f32_e32 v0, v181, v0
	v_cvt_pk_bf16_f32 v90, v172, v175
	v_cvt_pk_bf16_f32 v91, v173, v176
	v_cvt_pk_bf16_f32 v92, v174, v177
	v_cvt_pk_bf16_f32 v93, v170, v171
	s_nop 0
	v_permlane32_swap_b32_e32 v90, v92
	v_mfma_f32_32x32x16_bf16 v[114:129], v[192:195], v[228:231], v[114:129]
	v_exp_f32_e32 v192, v94
	v_exp_f32_e32 v193, v95
	v_exp_f32_e32 v194, v96
	v_exp_f32_e32 v195, v97
	v_add_f32_e32 v0, v192, v0
	v_add_f32_e32 v0, v193, v0
	v_add_f32_e32 v0, v194, v0
	v_mfma_f32_32x32x16_bf16 v[98:113], v[216:219], v[228:231], v[98:113]
	v_add_f32_e32 v0, v195, v0
	v_mov_b32_e32 v216, v0
	s_nop 1
	v_permlane32_swap_b32_e32 v0, v216
	v_cvt_pk_bf16_f32 v94, v166, v168
	v_cvt_pk_bf16_f32 v95, v167, v169
	v_cvt_pk_bf16_f32 v96, v162, v164
	v_cvt_pk_bf16_f32 v97, v163, v165
	v_cvt_pk_bf16_f32 v174, v82, v83
	v_cvt_pk_bf16_f32 v175, v84, v85
	v_cvt_pk_bf16_f32 v176, v86, v87
	v_cvt_pk_bf16_f32 v177, v88, v89
	v_cvt_pk_bf16_f32 v178, v178, v179
	v_cvt_pk_bf16_f32 v179, v180, v181
	v_cvt_pk_bf16_f32 v180, v192, v193
	v_cvt_pk_bf16_f32 v181, v194, v195
	v_permlane32_swap_b32_e32 v91, v93
	v_permlane32_swap_b32_e32 v94, v96
	v_permlane32_swap_b32_e32 v95, v97
	v_permlane32_swap_b32_e32 v174, v176
	v_permlane32_swap_b32_e32 v175, v177
	v_permlane32_swap_b32_e32 v178, v180
	v_permlane32_swap_b32_e32 v179, v181
	v_lshl_add_u64 v[196:197], s[70:71], 0, v[190:191]
	s_mov_b32 s0, 0x60e0000
	v_add_co_u32_e32 v82, vcc, s0, v196
	v_lshl_add_u64 v[194:195], s[70:71], 0, v[186:187]
	s_nop 0
	v_addc_co_u32_e32 v83, vcc, 0, v197, vcc
	s_mov_b32 s0, 0xe1c4000
	global_load_dwordx4 v[162:165], v[82:83], off
	global_load_dwordx4 v[166:169], v[82:83], off offset:128
	v_add_co_u32_e32 v82, vcc, s0, v194
	v_lshl_add_u64 v[192:193], s[70:71], 0, v[188:189]
	s_nop 0
	v_addc_co_u32_e32 v83, vcc, 0, v195, vcc
	s_mov_b32 s0, 0xa150000
	v_add_co_u32_e32 v84, vcc, s0, v192
	s_mov_b32 s0, 0xa158000
	s_nop 0
	v_addc_co_u32_e32 v85, vcc, 0, v193, vcc
	v_add_co_u32_e32 v86, vcc, s0, v192
	global_load_dwordx4 v[170:173], v[82:83], off
	s_nop 0
	global_load_dwordx4 v[82:85], v[84:85], off
	v_addc_co_u32_e32 v87, vcc, 0, v193, vcc
	global_load_dwordx4 v[86:89], v[86:87], off
	ds_read_b64_tr_b16 v[218:219], v207 offset:0
	ds_read_b64_tr_b16 v[220:221], v207 offset:0x800
	ds_read_b64_tr_b16 v[222:223], v207 offset:0x1000
	ds_read_b64_tr_b16 v[224:225], v207 offset:0x1800
	ds_read_b64_tr_b16 v[226:227], v207 offset:0x2000
	ds_read_b64_tr_b16 v[228:229], v207 offset:0x2800
	ds_read_b64_tr_b16 v[230:231], v207 offset:0x3000
	ds_read_b64_tr_b16 v[232:233], v207 offset:0x3800
	ds_read_b64_tr_b16 v[234:235], v207 offset:0x200
	ds_read_b64_tr_b16 v[236:237], v207 offset:0xa00
	ds_read_b64_tr_b16 v[238:239], v207 offset:0x1200
	ds_read_b64_tr_b16 v[240:241], v207 offset:0x1a00
	ds_read_b64_tr_b16 v[242:243], v207 offset:0x2200
	ds_read_b64_tr_b16 v[244:245], v207 offset:0x2a00
	ds_read_b64_tr_b16 v[246:247], v207 offset:0x3200
	ds_read_b64_tr_b16 v[248:249], v207 offset:0x3a00
	s_nop 0
	s_waitcnt lgkmcnt(8)
	s_nop 0
	v_mfma_f32_32x32x16_bf16 v[50:65], v[90:93], v[218:221], v[50:65]
	ds_read_b64_tr_b16 v[218:219], v207 offset:0x400
	ds_read_b64_tr_b16 v[220:221], v207 offset:0xc00
	v_mfma_f32_32x32x16_bf16 v[50:65], v[94:97], v[222:225], v[50:65]
	ds_read_b64_tr_b16 v[222:223], v207 offset:0x1400
	ds_read_b64_tr_b16 v[224:225], v207 offset:0x1c00
	v_mfma_f32_32x32x16_bf16 v[50:65], v[174:177], v[226:229], v[50:65]
	ds_read_b64_tr_b16 v[226:227], v207 offset:0x2400
	ds_read_b64_tr_b16 v[228:229], v207 offset:0x2c00
	v_mfma_f32_32x32x16_bf16 v[50:65], v[178:181], v[230:233], v[50:65]
	ds_read_b64_tr_b16 v[230:231], v207 offset:0x3400
	ds_read_b64_tr_b16 v[232:233], v207 offset:0x3c00
	s_waitcnt lgkmcnt(8)
	s_nop 0
	v_mfma_f32_32x32x16_bf16 v[34:49], v[90:93], v[234:237], v[34:49]
	ds_read_b64_tr_b16 v[234:235], v207 offset:0x600
	ds_read_b64_tr_b16 v[236:237], v207 offset:0xe00
	v_mfma_f32_32x32x16_bf16 v[34:49], v[94:97], v[238:241], v[34:49]
	ds_read_b64_tr_b16 v[238:239], v207 offset:0x1600
	ds_read_b64_tr_b16 v[240:241], v207 offset:0x1e00
	v_mfma_f32_32x32x16_bf16 v[34:49], v[174:177], v[242:245], v[34:49]
	ds_read_b64_tr_b16 v[242:243], v207 offset:0x2600
	ds_read_b64_tr_b16 v[244:245], v207 offset:0x2e00
	v_mfma_f32_32x32x16_bf16 v[34:49], v[178:181], v[246:249], v[34:49]
	ds_read_b64_tr_b16 v[246:247], v207 offset:0x3600
	ds_read_b64_tr_b16 v[248:249], v207 offset:0x3e00
	s_waitcnt lgkmcnt(8)
	s_nop 0
	s_waitcnt lgkmcnt(0)
	v_mfma_f32_32x32x16_bf16 v[18:33], v[90:93], v[218:221], v[18:33]
	v_mfma_f32_32x32x16_bf16 v[2:17], v[90:93], v[234:237], v[2:17]
	v_max_f32_e32 v90, v115, v115
	v_max_f32_e32 v91, v114, v114
	v_max_f32_e32 v90, v91, v90
	v_max3_f32 v90, v90, v116, v117
	v_max3_f32 v90, v90, v118, v119
	v_max3_f32 v90, v90, v120, v121
	v_max3_f32 v90, v90, v122, v123
	v_mfma_f32_32x32x16_bf16 v[18:33], v[94:97], v[222:225], v[18:33]
	v_max3_f32 v90, v90, v124, v125
	v_max3_f32 v90, v90, v126, v127
	v_max3_f32 v90, v90, v128, v129
	v_max3_f32 v90, v90, v98, v99
	v_max3_f32 v90, v90, v100, v101
	v_max3_f32 v90, v90, v102, v103
	v_max3_f32 v90, v90, v104, v105
	v_mfma_f32_32x32x16_bf16 v[2:17], v[94:97], v[238:241], v[2:17]
	v_max3_f32 v90, v90, v106, v107
	v_max3_f32 v90, v90, v108, v109
	v_max3_f32 v90, v90, v110, v111
	v_max3_f32 v90, v90, v112, v113
	v_mov_b32_e32 v91, v90
	s_nop 1
	v_permlane32_swap_b32_e32 v90, v91
	v_mfma_f32_32x32x16_bf16 v[18:33], v[174:177], v[226:229], v[18:33]
	v_max_f32_e32 v90, v90, v91
	v_cmp_lt_f32_e32 vcc, s75, v90
	v_mfma_f32_32x32x16_bf16 v[2:17], v[174:177], v[242:245], v[2:17]
	v_mfma_f32_32x32x16_bf16 v[18:33], v[178:181], v[230:233], v[18:33]
	v_mfma_f32_32x32x16_bf16 v[2:17], v[178:181], v[246:249], v[2:17]
	s_cbranch_vccnz .LBB0_1390
	v_mov_b32_e32 v217, 1.0
	s_branch .LBB0_1377

; template <bool START>
; __device__ __forceinline__ void partialSM(f32x16& p0, f32x16& p1, float& mhat, f32x16& negm, float& alpha) {
;   float pmax = p0[0];
; #pragma unroll
;   for (int r = 1; r < 16; ++r) pmax = fmaxf(pmax, p0[r]);
; #pragma unroll
;   for (int r = 0; r < 16; ++r) pmax = fmaxf(pmax, p1[r]);
;   { auto rr = __builtin_amdgcn_permlane32_swap(__float_as_uint(pmax), __float_as_uint(pmax), false, false);
;     pmax = fmaxf(__uint_as_float(rr[0]), __uint_as_float(rr[1])); }
;   alpha = 1.f;
;   if (START || __builtin_expect(__any(pmax > THRL), 0)) {
;     const float dl = START ? pmax : fmaxf(pmax, 0.f);
;     mhat += dl;
; #pragma unroll
;     for (int r = 0; r < 16; ++r) { p0[r] -= dl; p1[r] -= dl; }
; #pragma unroll
;     for (int r = 0; r < 16; ++r) negm[r] = -mhat;
;     asm volatile("" : "+v"(negm));
;     if (!START) alpha = __builtin_amdgcn_exp2f(-dl);
;   }
; #pragma unroll
;   for (int r = 0; r < 16; ++r) p0[r] = __builtin_amdgcn_exp2f(p0[r]);
; }
; __device__ __forceinline__ void finishSM(f32x16& p0, f32x16& p1, float alpha, float& l_reg, bf16x8& pa0, bf16x8& pa1, bf16x8& pa2, bf16x8& pa3) {
; #pragma unroll
;   for (int r = 0; r < 16; ++r) p1[r] = __builtin_amdgcn_exp2f(p1[r]);
;   float ps = 0;
; #pragma unroll
;   for (int r = 0; r < 16; ++r) ps += p0[r];
; #pragma unroll
;   for (int r = 0; r < 16; ++r) ps += p1[r];
;   { auto rr = __builtin_amdgcn_permlane32_swap(__float_as_uint(ps), __float_as_uint(ps), false, false);
;     ps = __uint_as_float(rr[0]) + __uint_as_float(rr[1]); }
;   l_reg = l_reg * alpha + ps;
;     ...
;   PK4(p0, 0, pa0); PK4(p0, 8, pa1); PK4(p1, 0, pa2); PK4(p1, 8, pa3);
;     ...
; }
; __device__ __forceinline__ void kmask(f32x16& p0, f32x16& p1, int nv, int hi) {
; #pragma unroll
;   for (int r = 0; r < 16; ++r) { const int k = crow(r, hi); if (k >= nv) p0[r] = -1e30f; if (k + 32 >= nv) p1[r] = -1e30f; }
; }
; __device__ __forceinline__ void pv_d0(f32x16* o, int vb, bf16x8 pa0, bf16x8 pa1, bf16x8 pa2, bf16x8 pa3) {
;   VF fa, fb;
;   pv_rd<0>(fa, vb);
;   pv_rd<1>(fb, vb); PV_WAIT(8, fa); pv_mm(o[0], fa, pa0, pa1, pa2, pa3);
;   pv_rd<2>(fa, vb); PV_WAIT(8, fb); pv_mm(o[1], fb, pa0, pa1, pa2, pa3);
;   pv_rd<3>(fb, vb); PV_WAIT(8, fa); pv_mm(o[2], fa, pa0, pa1, pa2, pa3);
;   PV_WAIT(0, fb); pv_mm(o[3], fb, pa0, pa1, pa2, pa3);
; }
.LBB0_1379:
	v_add_co_u32_e32 v98, vcc, 0xa160000, v192
	s_nop 1
	v_addc_co_u32_e32 v99, vcc, 0, v193, vcc
	v_add_co_u32_e32 v102, vcc, 0xa168000, v192
	s_nop 1
	v_addc_co_u32_e32 v103, vcc, 0, v193, vcc
	global_load_dwordx4 v[98:101], v[98:99], off
	s_nop 0
	global_load_dwordx4 v[102:105], v[102:103], off
	ds_read_b64_tr_b16 v[192:193], v213 offset:0
	ds_read_b64_tr_b16 v[194:195], v213 offset:0x800
	ds_read_b64_tr_b16 v[220:221], v213 offset:0x1000
	ds_read_b64_tr_b16 v[222:223], v213 offset:0x1800
	ds_read_b64_tr_b16 v[224:225], v213 offset:0x2000
	ds_read_b64_tr_b16 v[226:227], v213 offset:0x2800
	ds_read_b64_tr_b16 v[228:229], v213 offset:0x3000
	ds_read_b64_tr_b16 v[230:231], v213 offset:0x3800
	ds_read_b64_tr_b16 v[232:233], v213 offset:0x200
	ds_read_b64_tr_b16 v[234:235], v213 offset:0xa00
	ds_read_b64_tr_b16 v[236:237], v213 offset:0x1200
	ds_read_b64_tr_b16 v[238:239], v213 offset:0x1a00
	ds_read_b64_tr_b16 v[240:241], v213 offset:0x2200
	ds_read_b64_tr_b16 v[242:243], v213 offset:0x2a00
	ds_read_b64_tr_b16 v[244:245], v213 offset:0x3200
	ds_read_b64_tr_b16 v[246:247], v213 offset:0x3a00
	s_nop 0
	s_waitcnt lgkmcnt(8)
	s_cmp_lg_u32 s97, s91
	v_mfma_f32_32x32x16_bf16 v[50:65], v[106:109], v[192:195], v[50:65]
	ds_read_b64_tr_b16 v[192:193], v213 offset:0x400
	ds_read_b64_tr_b16 v[194:195], v213 offset:0xc00
	v_mfma_f32_32x32x16_bf16 v[50:65], v[110:113], v[220:223], v[50:65]
	ds_read_b64_tr_b16 v[220:221], v213 offset:0x1400
	ds_read_b64_tr_b16 v[222:223], v213 offset:0x1c00
	v_mfma_f32_32x32x16_bf16 v[50:65], v[174:177], v[224:227], v[50:65]
	ds_read_b64_tr_b16 v[224:225], v213 offset:0x2400
	ds_read_b64_tr_b16 v[226:227], v213 offset:0x2c00
	v_mfma_f32_32x32x16_bf16 v[50:65], v[178:181], v[228:231], v[50:65]
	ds_read_b64_tr_b16 v[228:229], v213 offset:0x3400
	ds_read_b64_tr_b16 v[230:231], v213 offset:0x3c00
	s_waitcnt lgkmcnt(8)
	s_nop 0
	v_mfma_f32_32x32x16_bf16 v[34:49], v[106:109], v[232:235], v[34:49]
	ds_read_b64_tr_b16 v[232:233], v213 offset:0x600
	ds_read_b64_tr_b16 v[234:235], v213 offset:0xe00
	v_mfma_f32_32x32x16_bf16 v[34:49], v[110:113], v[236:239], v[34:49]
	ds_read_b64_tr_b16 v[236:237], v213 offset:0x1600
	ds_read_b64_tr_b16 v[238:239], v213 offset:0x1e00
	v_mfma_f32_32x32x16_bf16 v[34:49], v[174:177], v[240:243], v[34:49]
	ds_read_b64_tr_b16 v[240:241], v213 offset:0x2600
	ds_read_b64_tr_b16 v[242:243], v213 offset:0x2e00
	v_mfma_f32_32x32x16_bf16 v[34:49], v[178:181], v[244:247], v[34:49]
	ds_read_b64_tr_b16 v[244:245], v213 offset:0x3600
	ds_read_b64_tr_b16 v[246:247], v213 offset:0x3e00
	s_waitcnt lgkmcnt(8)
	s_nop 0
	s_waitcnt lgkmcnt(0)
	v_mfma_f32_32x32x16_bf16 v[18:33], v[106:109], v[192:195], v[18:33]
	v_mfma_f32_32x32x16_bf16 v[2:17], v[106:109], v[232:235], v[2:17]
	v_max_f32_e32 v106, v115, v115
	v_max_f32_e32 v107, v114, v114
	v_max_f32_e32 v106, v107, v106
	v_max3_f32 v106, v106, v116, v117
	v_max3_f32 v106, v106, v118, v119
	v_mfma_f32_32x32x16_bf16 v[18:33], v[110:113], v[220:223], v[18:33]
	v_max3_f32 v106, v106, v120, v121
	v_max3_f32 v106, v106, v122, v123
	v_max3_f32 v106, v106, v124, v125
	v_max3_f32 v106, v106, v126, v127
	v_max3_f32 v106, v106, v128, v129
	v_mfma_f32_32x32x16_bf16 v[2:17], v[110:113], v[236:239], v[2:17]
	v_max3_f32 v106, v106, v82, v83
	v_max3_f32 v106, v106, v84, v85
	v_max3_f32 v106, v106, v86, v87
	v_max3_f32 v106, v106, v88, v89
	v_max3_f32 v106, v106, v90, v91
	v_mfma_f32_32x32x16_bf16 v[18:33], v[174:177], v[224:227], v[18:33]
	v_max3_f32 v106, v106, v92, v93
	v_max3_f32 v106, v106, v94, v95
	v_max3_f32 v106, v106, v96, v97
	v_mfma_f32_32x32x16_bf16 v[2:17], v[174:177], v[240:243], v[2:17]
	v_mov_b32_e32 v107, v106
	s_nop 1
	v_permlane32_swap_b32_e32 v106, v107
	v_mfma_f32_32x32x16_bf16 v[18:33], v[178:181], v[228:231], v[18:33]
	v_max_f32_e32 v107, v106, v107
	v_cmp_lt_f32_e32 vcc, s75, v107
	v_mov_b32_e32 v106, 1.0
	v_mfma_f32_32x32x16_bf16 v[2:17], v[178:181], v[244:247], v[2:17]
	s_cbranch_scc1 .LBB0_1381
	v_cndmask_b32_e64 v129, v198, v129, s[4:5]
	v_cndmask_b32_e64 v128, v198, v128, s[8:9]
	v_cndmask_b32_e64 v127, v198, v127, s[10:11]
	v_cndmask_b32_e64 v126, v198, v126, s[12:13]
	v_cndmask_b32_e64 v125, v198, v125, s[14:15]
	v_cndmask_b32_e64 v124, v198, v124, s[16:17]
	v_cndmask_b32_e64 v123, v198, v123, s[18:19]
	v_cndmask_b32_e64 v122, v198, v122, s[20:21]
	v_cndmask_b32_e64 v121, v198, v121, s[22:23]
	v_cndmask_b32_e64 v120, v198, v120, s[24:25]
	v_cndmask_b32_e64 v119, v198, v119, s[26:27]
	v_cndmask_b32_e64 v118, v198, v118, s[28:29]
	v_cndmask_b32_e64 v117, v198, v117, s[30:31]
	v_cndmask_b32_e64 v116, v198, v116, s[34:35]
	v_cndmask_b32_e64 v115, v198, v115, s[36:37]
	v_cndmask_b32_e64 v114, v198, v114, s[38:39]
	v_cndmask_b32_e64 v97, v198, v97, s[6:7]
	v_cndmask_b32_e64 v96, v198, v96, s[40:41]
	v_cndmask_b32_e64 v95, v198, v95, s[42:43]
	v_cndmask_b32_e64 v94, v198, v94, s[44:45]
	v_cndmask_b32_e64 v93, v198, v93, s[46:47]
	v_cndmask_b32_e64 v92, v198, v92, s[48:49]
	v_cndmask_b32_e64 v91, v198, v91, s[50:51]
	v_cndmask_b32_e64 v90, v198, v90, s[52:53]
	v_cndmask_b32_e64 v89, v198, v89, s[54:55]
	v_cndmask_b32_e64 v88, v198, v88, s[56:57]
	v_cndmask_b32_e64 v87, v198, v87, s[58:59]
	v_cndmask_b32_e64 v86, v198, v86, s[60:61]
	v_cndmask_b32_e64 v85, v198, v85, s[62:63]
	v_cndmask_b32_e64 v84, v198, v84, s[64:65]
	v_cndmask_b32_e64 v83, v198, v83, s[66:67]
	v_cndmask_b32_e64 v82, v198, v82, s[68:69]
	v_max_f32_e32 v106, v115, v115
	v_max_f32_e32 v107, v114, v114
	v_max_f32_e32 v106, v107, v106
	v_max3_f32 v106, v106, v116, v117
	v_max3_f32 v106, v106, v118, v119
	v_max3_f32 v106, v106, v120, v121
	v_max3_f32 v106, v106, v122, v123
	v_max3_f32 v106, v106, v124, v125
	v_max3_f32 v106, v106, v126, v127
	v_max3_f32 v106, v106, v128, v129
	v_max3_f32 v106, v106, v82, v83
	v_max3_f32 v106, v106, v84, v85
	v_max3_f32 v106, v106, v86, v87
	v_max3_f32 v106, v106, v88, v89
	v_max3_f32 v106, v106, v90, v91
	v_max3_f32 v106, v106, v92, v93
	v_max3_f32 v106, v106, v94, v95
	v_max3_f32 v106, v106, v96, v97
	v_mov_b32_e32 v107, v106
	s_nop 1
	v_permlane32_swap_b32_e32 v106, v107
	v_max_f32_e32 v107, v106, v107
	v_cmp_lt_f32_e32 vcc, s75, v107
	v_mov_b32_e32 v106, 1.0
